# DSA phase: runs (combo, 64-query chunk) handed out dynamically, largest first, from one atomic queue per blockIdx%8 group instead of the static two-units-per-workgroup split
# speedup vs baseline: 1.0144x; 1.0039x over previous
; #define LAS __attribute__((address_space(3)))
; #define LDS_WAIT() asm volatile("s_waitcnt lgkmcnt(0)" ::: "memory")
; __global__ void __launch_bounds__(NWAVES * 64, 2) fwd_megakernel(Args args) {
;     ...
;                 { LAS float* blw = (LAS float*)(wl + 12288);
; #pragma unroll
;                   for (int i = 0; i < 8; ++i) blw[lane + 64 * i] = LOG2E * args.in[I_RELB][lane + 64 * i];
;                   LDS_WAIT(); }
;                 for (int rep = 0; rep < REP_DSA; ++rep)
;                 if ((G & 7) == 0) { const int x = blockIdx.x & 7; const int nxw = (G >> 3) * NWAVES; const int wx = (blockIdx.x >> 3) * NWAVES + wave;
;                     for (int i = wx; i < 2 * SEQ; i += nxw) { const int combo = x + 8 * (i / SEQ);
;     ...
;  dsa_unit(QKV, SEL, AO, combo >> 2, combo & 3, i % SEQ, wl, lane);
;     ...
;  } }
;                 else { for (int i = gw; i < 16 * SEQ; i += ngw) { const int combo = i / SEQ;
;     ...
;  dsa_unit(QKV, SEL, AO, combo >> 2, combo & 3, i % SEQ, wl, lane);
;     ...
;  } }
.Ldsa_new:
	v_readfirstlane_b32 s0, v207
	v_readlane_b32 s1, v251, 14
	v_readlane_b32 s12, v251, 0
	v_readlane_b32 s13, v251, 1
	s_lshr_b32 s0, s0, 6
	v_readlane_b32 s2, v254, 3
	s_nop 3
	s_lshr_b32 s2, s2, 1
	s_lshl_b32 s2, s2, 2
	s_and_b32 s3, s1, 7
	s_add_u32 s3, s3, 33
	s_lshl_b32 s3, s3, 8
	s_add_u32 s2, s2, s3
	s_add_u32 s2, s62, s2
	s_addc_u32 s3, s63, 0
	s_mov_b32 s16, 0x88000
	s_mov_b32 s17, 0
	s_movk_i32 s23, 0x2200
	v_lshlrev_b32_e32 v178, 2, v207
	s_nop 4
	global_load_dword v179, v178, s[12:13]
	v_and_b32_e32 v64, 31, v206
	v_lshrrev_b32_e32 v65, 5, v206
	v_lshlrev_b32_e32 v175, 3, v65
	v_and_b32_e32 v66, 19, v64
	v_lshrrev_b32_e32 v67, 1, v64
	v_and_b32_e32 v67, 4, v67
	v_lshlrev_b32_e32 v68, 1, v64
	v_and_b32_e32 v68, 8, v68
	v_or3_b32 v66, v66, v67, v68
	v_mul_u32_u24_e32 v66, 0x110, v66
	v_lshl_add_u32 v66, v65, 4, v66
	v_add_u32_e32 v164, 0x4800, v66
	v_bfe_u32 v66, v206, 2, 2
	v_or_b32_e32 v66, v175, v66
	v_mul_u32_u24_e32 v66, 0x120, v66
	v_and_b32_e32 v67, 16, v206
	v_and_b32_e32 v68, 3, v206
	v_lshl_or_b32 v67, v68, 2, v67
	v_lshl_add_u32 v165, v67, 1, v66
	v_lshrrev_b32_e32 v66, 4, v207
	v_and_b32_e32 v67, 15, v207
	v_lshlrev_b32_e32 v67, 4, v67
	v_mul_u32_u24_e32 v68, 0x110, v66
	v_add_u32_e32 v68, v68, v67
	v_add_u32_e32 v166, 0x4800, v68
	v_mul_u32_u24_e32 v68, 0x120, v66
	v_add_u32_e32 v167, v68, v67
	s_waitcnt vmcnt(0)
	v_mul_f32_e32 v179, 0x3fb8aa3b, v179
	v_add_u32_e32 v178, 0x19800, v178
	ds_write_b32 v178, v179
	v_readlane_b32 s46, v251, 19
	v_readlane_b32 s47, v251, 20
	s_mul_i32 s45, s0, 0x2200
	s_add_u32 s24, s45, 0x8c00
	s_add_u32 s25, s45, 0x12c00
	s_cmp_lt_u32 s0, 4
	s_cselect_b32 s45, s24, s25
	s_lshl_b32 s44, s0, 3
	v_mov_b32_e32 v132, 0x23c00
	v_mov_b32_e32 v133, 1
	s_cmp_lg_u32 s0, 0
	s_cbranch_scc1 .Ldsa_f0
	s_mov_b64 exec, 1
	global_atomic_add v131, v183, v133, s[2:3] sc0
	s_waitcnt vmcnt(0)
	ds_write_b32 v132, v131
	s_mov_b64 exec, -1
.Ldsa_f0:
	s_waitcnt lgkmcnt(0)
	s_barrier
	ds_read_b32 v131, v132
	s_waitcnt lgkmcnt(0)
	v_readfirstlane_b32 s21, v131
	s_nop 3
.Ldsa_run:
	s_cmpk_ge_u32 s21, 0x80
	s_cbranch_scc1 .Ldsa_done
	s_and_b32 s24, s1, 7
	s_and_b32 s25, s21, 1
	s_lshl_b32 s25, s25, 3
	s_add_u32 s24, s24, s25
	s_lshr_b32 s4, s24, 2
	s_lshl_b32 s4, s4, 12
	s_and_b32 s5, s24, 3
	s_lshr_b32 s6, s21, 1
	s_sub_u32 s6, 63, s6
	s_cmp_lg_u32 s0, 0
	s_cbranch_scc1 .Ldsa_f1
	v_mov_b32_e32 v133, 1
	s_mov_b64 exec, 1
	global_atomic_add v131, v183, v133, s[2:3] sc0
	s_mov_b64 exec, -1
.Ldsa_f1:
	s_lshl_b32 s7, s6, 6
	s_add_u32 s8, s6, 1
	s_lshl_b32 s18, s8, 6
	s_min_u32 s18, s18, 0x100
	s_add_u32 s24, s4, s7
	s_add_u32 s24, s24, s44
	s_lshl_b32 s24, s24, 10
	s_add_u32 s14, s46, s24
	s_addc_u32 s15, s47, 0
	s_add_u32 s40, s14, 0x1000
	s_addc_u32 s41, s15, 0
	s_lshr_b32 s43, s18, 6
	v_lshlrev_b32_e32 v178, 2, v206
	global_load_dword v0, v178, s[14:15] offset:0
	global_load_dword v1, v178, s[14:15] offset:1024
	global_load_dword v2, v178, s[14:15] offset:2048
	global_load_dword v3, v178, s[14:15] offset:3072
	global_load_dword v4, v178, s[40:41] offset:0
	global_load_dword v5, v178, s[40:41] offset:1024
	global_load_dword v6, v178, s[40:41] offset:2048
	global_load_dword v7, v178, s[40:41] offset:3072
	s_cmp_gt_u32 s43, 1
	s_cbranch_scc0 .Ldsa_selld_end
	global_load_dword v8, v178, s[14:15] offset:256
	global_load_dword v9, v178, s[14:15] offset:1280
	global_load_dword v10, v178, s[14:15] offset:2304
	global_load_dword v11, v178, s[14:15] offset:3328
	global_load_dword v12, v178, s[40:41] offset:256
	global_load_dword v13, v178, s[40:41] offset:1280
	global_load_dword v14, v178, s[40:41] offset:2304
	global_load_dword v15, v178, s[40:41] offset:3328
	s_cmp_gt_u32 s43, 2
	s_cbranch_scc0 .Ldsa_selld_end
	global_load_dword v16, v178, s[14:15] offset:512
	global_load_dword v17, v178, s[14:15] offset:1536
	global_load_dword v18, v178, s[14:15] offset:2560
	global_load_dword v19, v178, s[14:15] offset:3584
	global_load_dword v20, v178, s[40:41] offset:512
	global_load_dword v21, v178, s[40:41] offset:1536
	global_load_dword v22, v178, s[40:41] offset:2560
	global_load_dword v23, v178, s[40:41] offset:3584
	s_cmp_gt_u32 s43, 3
	s_cbranch_scc0 .Ldsa_selld_end
	global_load_dword v24, v178, s[14:15] offset:768
	global_load_dword v25, v178, s[14:15] offset:1792
	global_load_dword v26, v178, s[14:15] offset:2816
	global_load_dword v27, v178, s[14:15] offset:3840
	global_load_dword v28, v178, s[40:41] offset:768
	global_load_dword v29, v178, s[40:41] offset:1792
	global_load_dword v30, v178, s[40:41] offset:2816
	global_load_dword v31, v178, s[40:41] offset:3840
; #define LAS __attribute__((address_space(3)))
; __device__ __forceinline__ int t5_bucket(int rel) {
;     const int nabs = rel < 0 ? -rel : rel;
;     int bk = nabs;
;     if (nabs >= 8) bk = 8 + (nabs >= 12) + (nabs >= 16) + (nabs >= 23) + (nabs >= 32) + (nabs >= 46) + (nabs >= 64) + (nabs >= 91);
;     return bk + (rel > 0 ? 16 : 0);
; }
; __device__ __forceinline__ void dsa_unit(const bf16* QB, const int* SEL, bf16* AO, int b, int kvh, int t, LAS unsigned char* wl, int lane) {
;     const size_t rowbase = (size_t)b * SEQ, row = rowbase + t;
;     const int n = lane & 31, hi = lane >> 5, l15 = lane & 15, kq = lane >> 4;
;     const int ce = ((t >> 6) + 1) << 6; const int nsel = ce < 256 ? ce : 256;
;     LAS unsigned char* buf = wl;
;     LAS bf16* pT = (LAS bf16*)(wl + 9216);
;     LAS int* il = (LAS int*)(wl + 11264);
;     const LAS float* bl = (const LAS float*)(wl + 12288) + kvh * 128;
;     int sidx[8];
; #pragma unroll
;     for (int kb = 0; kb < 8; ++kb) { const int p = 32 * kb + n; sidx[kb] = (p < nsel) ? SEL[row * 256 + p] : 0; }
;     bf16x8 qf[4];
;     { const bf16* qp = QB + row * NBP + CQ + (kvh * 4 + (l15 & 3)) * 128 + 8 * kq;
; #pragma unroll
;       for (int ks = 0; ks < 4; ++ks) qf[ks] = *(const bf16x8*)(qp + 32 * ks); }
.Ldsa_selld_end:
	v_mov_b32_e32 v64, 0
	v_mov_b32_e32 v65, 0
	v_mov_b32_e32 v66, 0
	v_mov_b32_e32 v67, 0
	v_lshlrev_b32_e32 v179, 6, v206
	s_lshl_b32 s24, s0, 12
	s_add_u32 s24, s24, 0x11800
	v_add_u32_e32 v179, s24, v179
	ds_write_b128 v179, v[64:67] offset:0
	ds_write_b128 v179, v[64:67] offset:16
	ds_write_b128 v179, v[64:67] offset:32
	ds_write_b128 v179, v[64:67] offset:48
	v_lshrrev_b32_e32 v178, 4, v207
	v_add_u32_e32 v178, s4, v178
	v_and_b32_e32 v179, 15, v207
	v_lshlrev_b32_e32 v182, 4, v179
	s_lshl_b32 s24, s5, 8
	s_add_u32 s24, s24, 0x1000
	v_add_u32_e32 v182, s24, v182
	v_lshl_add_u64 v[160:161], s[78:79], 0, v[182:183]
	v_mad_u64_u32 v[160:161], s[12:13], v178, s23, v[160:161]
	s_mov_b32 s24, 0x44000
	s_mov_b32 s25, 0
	v_lshl_add_u64 v[162:163], v[160:161], 0, s[24:25]
	global_load_dwordx4 v[144:147], v[160:161], off
	global_load_dwordx4 v[148:151], v[160:161], off offset:1024
	global_load_dwordx4 v[152:155], v[162:163], off
	global_load_dwordx4 v[156:159], v[162:163], off offset:1024
	v_lshl_add_u64 v[160:161], v[160:161], 0, s[16:17]
	v_lshl_add_u64 v[162:163], v[162:163], 0, s[16:17]
	v_and_b32_e32 v64, 31, v206
	v_lshrrev_b32_e32 v65, 2, v64
	v_and_b32_e32 v66, 3, v64
	s_add_u32 s24, s44, s7
	s_add_u32 s24, s24, s4
	v_add_u32_e32 v178, s24, v65
	s_lshl_b32 s25, s5, 2
	v_add_u32_e32 v179, s25, v66
	v_lshlrev_b32_e32 v179, 8, v179
	v_lshl_add_u32 v182, v175, 1, v179
	v_lshl_add_u64 v[128:129], s[78:79], 0, v[182:183]
	v_mad_u64_u32 v[128:129], s[12:13], v178, s23, v[128:129]
	global_load_dwordx4 v[80:83], v[128:129], off offset:0
	global_load_dwordx4 v[84:87], v[128:129], off offset:32
	global_load_dwordx4 v[88:91], v[128:129], off offset:64
	global_load_dwordx4 v[92:95], v[128:129], off offset:96
	global_load_dwordx4 v[96:99], v[128:129], off offset:128
	global_load_dwordx4 v[100:103], v[128:129], off offset:160
	global_load_dwordx4 v[104:107], v[128:129], off offset:192
	global_load_dwordx4 v[108:111], v[128:129], off offset:224
	v_add_u32_e32 v178, s44, v65
	v_lshlrev_b32_e32 v172, 9, v178
	v_add_u32_e32 v172, 0x11800, v172
	s_add_u32 s24, s44, s7
	v_add_u32_e32 v178, s24, v65
	v_sub_u32_e32 v178, v175, v178
	v_add_u32_e32 v178, 0x80, v178
	v_lshlrev_b32_e32 v178, 2, v178
	v_lshl_add_u32 v177, v66, 10, v178
	v_add_u32_e32 v177, 0x1a400, v177
	s_sub_u32 s19, s24, 0x7a
	s_lshl_b32 s25, s5, 2
	v_add_u32_e32 v178, s25, v66
	v_lshlrev_b32_e32 v178, 7, v178
	v_add_u32_e32 v176, 0x1983c, v178
	ds_read_b32 v176, v176
	v_and_b32_e32 v64, 0xff, v207
	v_subrev_u32_e32 v65, 0x80, v64
	v_sub_u32_e32 v66, 0, v65
	v_max_i32_e32 v66, v65, v66
	v_mov_b32_e32 v67, 8
	v_cmp_le_i32_e32 vcc, 12, v66
	s_nop 1
	v_addc_co_u32_e32 v67, vcc, 0, v67, vcc
	v_cmp_le_i32_e32 vcc, 16, v66
	s_nop 1
	v_addc_co_u32_e32 v67, vcc, 0, v67, vcc
	v_cmp_le_i32_e32 vcc, 23, v66
	s_nop 1
	v_addc_co_u32_e32 v67, vcc, 0, v67, vcc
	v_cmp_le_i32_e32 vcc, 32, v66
	s_nop 1
	v_addc_co_u32_e32 v67, vcc, 0, v67, vcc
	v_cmp_le_i32_e32 vcc, 46, v66
	s_nop 1
	v_addc_co_u32_e32 v67, vcc, 0, v67, vcc
	v_cmp_le_i32_e32 vcc, 64, v66
	s_nop 1
	v_addc_co_u32_e32 v67, vcc, 0, v67, vcc
	v_cmp_le_i32_e32 vcc, 91, v66
	s_nop 1
	v_addc_co_u32_e32 v67, vcc, 0, v67, vcc
	v_cmp_gt_i32_e32 vcc, 8, v66
	s_nop 1
	v_cndmask_b32_e32 v67, v67, v66, vcc
	v_add_u32_e32 v68, 16, v67
	v_cmp_lt_i32_e32 vcc, 0, v65
	s_nop 1
	v_cndmask_b32_e32 v67, v67, v68, vcc
	v_lshrrev_b32_e32 v68, 8, v207
	s_lshl_b32 s24, s5, 2
	v_add_u32_e32 v69, s24, v68
	v_lshl_add_u32 v69, v69, 5, v67
	v_lshlrev_b32_e32 v69, 2, v69
	v_add_u32_e32 v69, 0x19800, v69
	ds_read_b32 v70, v69
	ds_read_b32 v71, v69 offset:256
	v_lshl_add_u32 v72, v68, 8, v64
	v_lshlrev_b32_e32 v72, 2, v72
	v_add_u32_e32 v72, 0x1a400, v72
	s_waitcnt lgkmcnt(0)
	ds_write_b32 v72, v70
	ds_write_b32 v72, v71 offset:2048
	s_waitcnt vmcnt(0)
	s_cmp_lg_u32 s0, 0
	s_cbranch_scc1 .Ldsa_f2
	v_mov_b32_e32 v132, 0x23c00
	s_mov_b64 exec, 1
	ds_write_b32 v132, v131
	s_mov_b64 exec, -1
.Ldsa_f2:
	s_lshl_b32 s24, s0, 12
	s_add_u32 s24, s24, 0x11800
	v_lshrrev_b32_e32 v64, 3, v0
	v_and_b32_e32 v64, 0x1fc, v64
	v_add_u32_e32 v64, s24, v64
	v_lshlrev_b32_e64 v65, v0, 1
	ds_or_b32 v64, v65 offset:0
	v_lshrrev_b32_e32 v64, 3, v1
	v_and_b32_e32 v64, 0x1fc, v64
	v_add_u32_e32 v64, s24, v64
	v_lshlrev_b32_e64 v65, v1, 1
	ds_or_b32 v64, v65 offset:512
	v_lshrrev_b32_e32 v64, 3, v2
	v_and_b32_e32 v64, 0x1fc, v64
	v_add_u32_e32 v64, s24, v64
	v_lshlrev_b32_e64 v65, v2, 1
	ds_or_b32 v64, v65 offset:1024
	v_lshrrev_b32_e32 v64, 3, v3
	v_and_b32_e32 v64, 0x1fc, v64
	v_add_u32_e32 v64, s24, v64
	v_lshlrev_b32_e64 v65, v3, 1
	ds_or_b32 v64, v65 offset:1536
	v_lshrrev_b32_e32 v64, 3, v4
	v_and_b32_e32 v64, 0x1fc, v64
	v_add_u32_e32 v64, s24, v64
	v_lshlrev_b32_e64 v65, v4, 1
	ds_or_b32 v64, v65 offset:2048
	v_lshrrev_b32_e32 v64, 3, v5
	v_and_b32_e32 v64, 0x1fc, v64
	v_add_u32_e32 v64, s24, v64
	v_lshlrev_b32_e64 v65, v5, 1
	ds_or_b32 v64, v65 offset:2560
	v_lshrrev_b32_e32 v64, 3, v6
	v_and_b32_e32 v64, 0x1fc, v64
	v_add_u32_e32 v64, s24, v64
	v_lshlrev_b32_e64 v65, v6, 1
	ds_or_b32 v64, v65 offset:3072
	v_lshrrev_b32_e32 v64, 3, v7
	v_and_b32_e32 v64, 0x1fc, v64
	v_add_u32_e32 v64, s24, v64
	v_lshlrev_b32_e64 v65, v7, 1
	ds_or_b32 v64, v65 offset:3584
	s_cmp_gt_u32 s43, 1
	s_cbranch_scc0 .Ldsa_selor_end
; __device__ __forceinline__ void dsa_unit(const bf16* QB, const int* SEL, bf16* AO, int b, int kvh, int t, LAS unsigned char* wl, int lane) {
;     ...
;         const bool valid = (32 * kb + n) < nsel;
; #pragma unroll
;         for (int g = 0; g < 4; ++g) { const float raw = upper ? a1[g] : a0[g]; const float v = valid ? raw + bl[g * 32 + bk] : -__builtin_inff(); lg[kb][g] = v; mx[g] = __builtin_fmaxf(mx[g], v); }
;     ...
; #pragma unroll
;     for (int c = 0; c < 8; ++c) o[c] = (f32x4v){0.f, 0.f, 0.f, 0.f};
	v_lshrrev_b32_e32 v64, 3, v8
	v_and_b32_e32 v64, 0x1fc, v64
	v_add_u32_e32 v64, s24, v64
	v_lshlrev_b32_e64 v65, v8, 1
	ds_or_b32 v64, v65 offset:0
	v_lshrrev_b32_e32 v64, 3, v9
	v_and_b32_e32 v64, 0x1fc, v64
	v_add_u32_e32 v64, s24, v64
	v_lshlrev_b32_e64 v65, v9, 1
	ds_or_b32 v64, v65 offset:512
	v_lshrrev_b32_e32 v64, 3, v10
	v_and_b32_e32 v64, 0x1fc, v64
	v_add_u32_e32 v64, s24, v64
	v_lshlrev_b32_e64 v65, v10, 1
	ds_or_b32 v64, v65 offset:1024
	v_lshrrev_b32_e32 v64, 3, v11
	v_and_b32_e32 v64, 0x1fc, v64
	v_add_u32_e32 v64, s24, v64
	v_lshlrev_b32_e64 v65, v11, 1
	ds_or_b32 v64, v65 offset:1536
	v_lshrrev_b32_e32 v64, 3, v12
	v_and_b32_e32 v64, 0x1fc, v64
	v_add_u32_e32 v64, s24, v64
	v_lshlrev_b32_e64 v65, v12, 1
	ds_or_b32 v64, v65 offset:2048
	v_lshrrev_b32_e32 v64, 3, v13
	v_and_b32_e32 v64, 0x1fc, v64
	v_add_u32_e32 v64, s24, v64
	v_lshlrev_b32_e64 v65, v13, 1
	ds_or_b32 v64, v65 offset:2560
	v_lshrrev_b32_e32 v64, 3, v14
	v_and_b32_e32 v64, 0x1fc, v64
	v_add_u32_e32 v64, s24, v64
	v_lshlrev_b32_e64 v65, v14, 1
	ds_or_b32 v64, v65 offset:3072
	v_lshrrev_b32_e32 v64, 3, v15
	v_and_b32_e32 v64, 0x1fc, v64
	v_add_u32_e32 v64, s24, v64
	v_lshlrev_b32_e64 v65, v15, 1
	ds_or_b32 v64, v65 offset:3584
	s_cmp_gt_u32 s43, 2
	s_cbranch_scc0 .Ldsa_selor_end
	v_lshrrev_b32_e32 v64, 3, v16
	v_and_b32_e32 v64, 0x1fc, v64
	v_add_u32_e32 v64, s24, v64
	v_lshlrev_b32_e64 v65, v16, 1
	ds_or_b32 v64, v65 offset:0
	v_lshrrev_b32_e32 v64, 3, v17
	v_and_b32_e32 v64, 0x1fc, v64
	v_add_u32_e32 v64, s24, v64
	v_lshlrev_b32_e64 v65, v17, 1
	ds_or_b32 v64, v65 offset:512
	v_lshrrev_b32_e32 v64, 3, v18
	v_and_b32_e32 v64, 0x1fc, v64
	v_add_u32_e32 v64, s24, v64
	v_lshlrev_b32_e64 v65, v18, 1
	ds_or_b32 v64, v65 offset:1024
	v_lshrrev_b32_e32 v64, 3, v19
	v_and_b32_e32 v64, 0x1fc, v64
	v_add_u32_e32 v64, s24, v64
	v_lshlrev_b32_e64 v65, v19, 1
	ds_or_b32 v64, v65 offset:1536
	v_lshrrev_b32_e32 v64, 3, v20
	v_and_b32_e32 v64, 0x1fc, v64
	v_add_u32_e32 v64, s24, v64
	v_lshlrev_b32_e64 v65, v20, 1
	ds_or_b32 v64, v65 offset:2048
	v_lshrrev_b32_e32 v64, 3, v21
	v_and_b32_e32 v64, 0x1fc, v64
	v_add_u32_e32 v64, s24, v64
	v_lshlrev_b32_e64 v65, v21, 1
	ds_or_b32 v64, v65 offset:2560
	v_lshrrev_b32_e32 v64, 3, v22
	v_and_b32_e32 v64, 0x1fc, v64
	v_add_u32_e32 v64, s24, v64
	v_lshlrev_b32_e64 v65, v22, 1
	ds_or_b32 v64, v65 offset:3072
	v_lshrrev_b32_e32 v64, 3, v23
	v_and_b32_e32 v64, 0x1fc, v64
	v_add_u32_e32 v64, s24, v64
	v_lshlrev_b32_e64 v65, v23, 1
	ds_or_b32 v64, v65 offset:3584
	s_cmp_gt_u32 s43, 3
	s_cbranch_scc0 .Ldsa_selor_end
	v_lshrrev_b32_e32 v64, 3, v24
	v_and_b32_e32 v64, 0x1fc, v64
	v_add_u32_e32 v64, s24, v64
	v_lshlrev_b32_e64 v65, v24, 1
	ds_or_b32 v64, v65 offset:0
	v_lshrrev_b32_e32 v64, 3, v25
	v_and_b32_e32 v64, 0x1fc, v64
	v_add_u32_e32 v64, s24, v64
	v_lshlrev_b32_e64 v65, v25, 1
	ds_or_b32 v64, v65 offset:512
	v_lshrrev_b32_e32 v64, 3, v26
	v_and_b32_e32 v64, 0x1fc, v64
	v_add_u32_e32 v64, s24, v64
	v_lshlrev_b32_e64 v65, v26, 1
	ds_or_b32 v64, v65 offset:1024
	v_lshrrev_b32_e32 v64, 3, v27
	v_and_b32_e32 v64, 0x1fc, v64
	v_add_u32_e32 v64, s24, v64
	v_lshlrev_b32_e64 v65, v27, 1
	ds_or_b32 v64, v65 offset:1536
	v_lshrrev_b32_e32 v64, 3, v28
	v_and_b32_e32 v64, 0x1fc, v64
	v_add_u32_e32 v64, s24, v64
	v_lshlrev_b32_e64 v65, v28, 1
	ds_or_b32 v64, v65 offset:2048
	v_lshrrev_b32_e32 v64, 3, v29
	v_and_b32_e32 v64, 0x1fc, v64
	v_add_u32_e32 v64, s24, v64
	v_lshlrev_b32_e64 v65, v29, 1
	ds_or_b32 v64, v65 offset:2560
	v_lshrrev_b32_e32 v64, 3, v30
	v_and_b32_e32 v64, 0x1fc, v64
	v_add_u32_e32 v64, s24, v64
	v_lshlrev_b32_e64 v65, v30, 1
	ds_or_b32 v64, v65 offset:3072
	v_lshrrev_b32_e32 v64, 3, v31
	v_and_b32_e32 v64, 0x1fc, v64
	v_add_u32_e32 v64, s24, v64
	v_lshlrev_b32_e64 v65, v31, 1
	ds_or_b32 v64, v65 offset:3584
.Ldsa_selor_end:
	ds_write_b128 v166, v[144:147]
	ds_write_b128 v167, v[148:151]
	ds_write_b128 v166, v[152:155] offset:8704
	ds_write_b128 v167, v[156:159] offset:9216
	v_mov_b32_e32 v0, 0
	v_mov_b32_e32 v1, 0
	v_mov_b32_e32 v2, 0
	v_mov_b32_e32 v3, 0
	v_mov_b32_e32 v4, 0
	v_mov_b32_e32 v5, 0
	v_mov_b32_e32 v6, 0
	v_mov_b32_e32 v7, 0
	v_mov_b32_e32 v8, 0
	v_mov_b32_e32 v9, 0
	v_mov_b32_e32 v10, 0
	v_mov_b32_e32 v11, 0
	v_mov_b32_e32 v12, 0
	v_mov_b32_e32 v13, 0
	v_mov_b32_e32 v14, 0
	v_mov_b32_e32 v15, 0
	v_mov_b32_e32 v16, 0
	v_mov_b32_e32 v17, 0
	v_mov_b32_e32 v18, 0
	v_mov_b32_e32 v19, 0
	v_mov_b32_e32 v20, 0
	v_mov_b32_e32 v21, 0
	v_mov_b32_e32 v22, 0
	v_mov_b32_e32 v23, 0
	v_mov_b32_e32 v24, 0
	v_mov_b32_e32 v25, 0
	v_mov_b32_e32 v26, 0
	v_mov_b32_e32 v27, 0
	v_mov_b32_e32 v28, 0
	v_mov_b32_e32 v29, 0
	v_mov_b32_e32 v30, 0
	v_mov_b32_e32 v31, 0
	v_mov_b32_e32 v32, 0
	v_mov_b32_e32 v33, 0
	v_mov_b32_e32 v34, 0
	v_mov_b32_e32 v35, 0
	v_mov_b32_e32 v36, 0
	v_mov_b32_e32 v37, 0
	v_mov_b32_e32 v38, 0
	v_mov_b32_e32 v39, 0
	v_mov_b32_e32 v40, 0
	v_mov_b32_e32 v41, 0
	v_mov_b32_e32 v42, 0
	v_mov_b32_e32 v43, 0
	v_mov_b32_e32 v44, 0
	v_mov_b32_e32 v45, 0
	v_mov_b32_e32 v46, 0
	v_mov_b32_e32 v47, 0
	v_mov_b32_e32 v48, 0
	v_mov_b32_e32 v49, 0
	v_mov_b32_e32 v50, 0
	v_mov_b32_e32 v51, 0
	v_mov_b32_e32 v52, 0
	v_mov_b32_e32 v53, 0
	v_mov_b32_e32 v54, 0
	v_mov_b32_e32 v55, 0
	v_mov_b32_e32 v56, 0
	v_mov_b32_e32 v57, 0
	v_mov_b32_e32 v58, 0
	v_mov_b32_e32 v59, 0
	v_mov_b32_e32 v60, 0
	v_mov_b32_e32 v61, 0
	v_mov_b32_e32 v62, 0
	v_mov_b32_e32 v63, 0
	v_mov_b32_e32 v173, 0
	s_mov_b32 s9, 0
	s_mov_b32 s10, 0
	s_mov_b32 s11, 0x8c00
	s_waitcnt lgkmcnt(0)
	s_barrier
	s_mov_b32 s13, 0xf149f2ca
	ds_read_b32 v174, v172
	ds_read_b32 v182, v172 offset:4
	v_mov_b32_e32 v132, 0x23c00
	ds_read_b32 v131, v132
	s_waitcnt lgkmcnt(0)
	v_readfirstlane_b32 s35, v131
	v_lshrrev_b32_e32 v174, v175, v174
	v_bfe_i32 v178, v174, 0, 1
	v_bfi_b32 v64, v178, v176, s13
	v_bfe_i32 v179, v174, 1, 1
	v_bfi_b32 v65, v179, v176, s13
	v_bfe_i32 v178, v174, 2, 1
	v_bfi_b32 v66, v178, v176, s13
	v_bfe_i32 v179, v174, 3, 1
	v_bfi_b32 v67, v179, v176, s13
	v_bfe_i32 v178, v174, 4, 1
	v_bfi_b32 v68, v178, v176, s13
	v_bfe_i32 v179, v174, 5, 1
	v_bfi_b32 v69, v179, v176, s13
	v_bfe_i32 v178, v174, 6, 1
	v_bfi_b32 v70, v178, v176, s13
	v_bfe_i32 v179, v174, 7, 1
	v_bfi_b32 v71, v179, v176, s13
	v_bfe_i32 v178, v174, 16, 1
	v_bfi_b32 v72, v178, v176, s13
	v_bfe_i32 v179, v174, 17, 1
	v_bfi_b32 v73, v179, v176, s13
	v_bfe_i32 v178, v174, 18, 1
	v_bfi_b32 v74, v178, v176, s13
	v_bfe_i32 v179, v174, 19, 1
	v_bfi_b32 v75, v179, v176, s13
	v_bfe_i32 v178, v174, 20, 1
	v_bfi_b32 v76, v178, v176, s13
	v_bfe_i32 v179, v174, 21, 1
	v_bfi_b32 v77, v179, v176, s13
	v_bfe_i32 v178, v174, 22, 1
	v_bfi_b32 v78, v178, v176, s13
	v_bfe_i32 v179, v174, 23, 1
	v_bfi_b32 v79, v179, v176, s13

; #define LAS __attribute__((address_space(3)))
; __device__ __forceinline__ unsigned pk2(float lo, float hi) { return pg8::cvt_pk_bf16(lo, hi); }
; #define LDS_WAIT() asm volatile("s_waitcnt lgkmcnt(0)" ::: "memory")
; __device__ __forceinline__ s16x4 vtr(const LAS unsigned char* p) { return __builtin_bit_cast(s16x4, __builtin_amdgcn_ds_read_tr16_b64_v4i16((LAS s16x4*)p)); }
; __device__ __forceinline__ void dsa_unit(const bf16* QB, const int* SEL, bf16* AO, int b, int kvh, int t, LAS unsigned char* wl, int lane) {
;     ...
;         for (int ks = 0; ks < 4; ++ks) { const bf16x8 b0 = *(const LAS bf16x8*)(kfb + 64 * ks), b1 = *(const LAS bf16x8*)(kfb + 16 * 272 + 64 * ks);
;             a0 = __builtin_amdgcn_mfma_f32_16x16x32_bf16(qf[ks], b0, a0, 0, 0, 0); a1 = __builtin_amdgcn_mfma_f32_16x16x32_bf16(qf[ks], b1, a1, 0, 0, 0); }
;     ...
;         for (int kb = 0; kb < 8; ++kb) { const float e = __builtin_amdgcn_exp2f(lg[kb][g] - m); lg[kb][g] = e; s += e; }
;         s += __shfl_xor(s, 1); s += __shfl_xor(s, 2); s += __shfl_xor(s, 4); s += __shfl_xor(s, 8); s += __shfl_xor(s, 16);
;         const float inv = 1.0f / s;
; #pragma unroll
;         for (int kb = 0; kb < 8; ++kb) if ((kb >> 2) == hi) pT[g * 256 + 32 * kb + n] = (bf16)(pk2(lg[kb][g] * inv, 0.f) & 0xffffu);
;     }
;     f32x4v o[8];
; #pragma unroll
;     for (int c = 0; c < 8; ++c) o[c] = (f32x4v){0.f, 0.f, 0.f, 0.f};
;     const LAS unsigned char* vtb = buf + (8 * kq + (l15 >> 2)) * 288 + (lane & 3) * 8;
;     LAS unsigned char* vdst = buf + r4 * 288 + c16 * 16;
;     const LAS bf16* pfp = pT + (l15 & 3) * 256 + 8 * kq;
; #pragma unroll
;     for (int ch = 0; ch < 8; ++ch) {
; #pragma unroll
;         for (int i = 0; i < 8; ++i) *(LAS bf16x8*)(vdst + (4 * i) * 288) = vr[ch % 3][i];
;         if (ch + 3 < 8) {
; #pragma unroll
;             for (int i = 0; i < 8; ++i) vr[ch % 3][i] = *(const bf16x8*)(vg + (size_t)il[32 * (ch + 3) + 4 * i + r4] * NBP);
;         }
;         const bf16x8 pf = *(const LAS bf16x8*)(pfp + 32 * ch);
;         LDS_WAIT();
; #pragma unroll
;         for (int c = 0; c < 8; ++c) {
;             const s16x4 lo = vtr(vtb + c * 32), hh = vtr(vtb + 4 * 288 + c * 32);
;             o[c] = __builtin_amdgcn_mfma_f32_16x16x32_bf16(pf, (bf16x8){lo[0], lo[1], lo[2], lo[3], hh[0], hh[1], hh[2], hh[3]}, o[c], 0, 0, 0);
;         }
.Ldsa_farB:
	ds_read_b32 v174, v172 offset:8
	ds_read_b32 v182, v172 offset:12
	s_nop 1
	s_waitcnt lgkmcnt(5)
	v_mfma_f32_32x32x16_bf16 v[128:143], v[112:115], v[80:83], v[128:143]
	ds_read_b128 v[112:115], v168 offset:8832
	v_exp_f32_e32 v64, v64
	v_exp_f32_e32 v65, v65
	v_add_f32_e32 v173, v173, v64
	v_add_f32_e32 v173, v173, v65
	v_cvt_pk_bf16_f32 v64, v64, v65
	s_waitcnt lgkmcnt(5)
	v_mfma_f32_32x32x16_bf16 v[128:143], v[116:119], v[84:87], v[128:143]
	ds_read_b128 v[116:119], v168 offset:8864
	v_exp_f32_e32 v66, v66
	v_exp_f32_e32 v67, v67
	v_add_f32_e32 v173, v173, v66
	v_add_f32_e32 v173, v173, v67
	v_cvt_pk_bf16_f32 v65, v66, v67
	s_waitcnt lgkmcnt(5)
	v_mfma_f32_32x32x16_bf16 v[128:143], v[120:123], v[88:91], v[128:143]
	ds_read_b128 v[120:123], v168 offset:8896
	v_exp_f32_e32 v68, v68
	v_exp_f32_e32 v69, v69
	v_add_f32_e32 v173, v173, v68
	v_add_f32_e32 v173, v173, v69
	v_cvt_pk_bf16_f32 v66, v68, v69
	s_waitcnt lgkmcnt(5)
	v_mfma_f32_32x32x16_bf16 v[128:143], v[124:127], v[92:95], v[128:143]
	ds_read_b128 v[124:127], v168 offset:8928
	v_exp_f32_e32 v70, v70
	v_exp_f32_e32 v71, v71
	v_add_f32_e32 v173, v173, v70
	v_add_f32_e32 v173, v173, v71
	v_cvt_pk_bf16_f32 v67, v70, v71
	s_waitcnt lgkmcnt(3)
	v_mfma_f32_32x32x16_bf16 v[128:143], v[112:115], v[96:99], v[128:143]
	ds_read_b64_tr_b16 v[112:113], v169 offset:0
	ds_read_b64_tr_b16 v[114:115], v169 offset:1152
	v_exp_f32_e32 v72, v72
	v_exp_f32_e32 v73, v73
	v_add_f32_e32 v173, v173, v72
	v_add_f32_e32 v173, v173, v73
	v_cvt_pk_bf16_f32 v68, v72, v73
	s_waitcnt lgkmcnt(4)
	v_mfma_f32_32x32x16_bf16 v[128:143], v[116:119], v[100:103], v[128:143]
	ds_read_b64_tr_b16 v[116:117], v169 offset:64
	ds_read_b64_tr_b16 v[118:119], v169 offset:1216
	v_exp_f32_e32 v74, v74
	v_exp_f32_e32 v75, v75
	v_add_f32_e32 v173, v173, v74
	v_add_f32_e32 v173, v173, v75
	v_cvt_pk_bf16_f32 v69, v74, v75
	s_waitcnt lgkmcnt(5)
	v_mfma_f32_32x32x16_bf16 v[128:143], v[120:123], v[104:107], v[128:143]
	ds_read_b64_tr_b16 v[120:121], v169 offset:128
	ds_read_b64_tr_b16 v[122:123], v169 offset:1280
	v_exp_f32_e32 v76, v76
	v_exp_f32_e32 v77, v77
	v_add_f32_e32 v173, v173, v76
	v_add_f32_e32 v173, v173, v77
	v_cvt_pk_bf16_f32 v70, v76, v77
	s_waitcnt lgkmcnt(6)
	v_mfma_f32_32x32x16_bf16 v[128:143], v[124:127], v[108:111], v[128:143]
	ds_read_b64_tr_b16 v[124:125], v169 offset:192
	ds_read_b64_tr_b16 v[126:127], v169 offset:1344
	v_exp_f32_e32 v78, v78
	v_exp_f32_e32 v79, v79
	v_add_f32_e32 v173, v173, v78
	v_add_f32_e32 v173, v173, v79
	v_cvt_pk_bf16_f32 v71, v78, v79
	s_waitcnt lgkmcnt(6)
	v_mfma_f32_32x32x16_bf16 v[0:15], v[64:67], v[112:115], v[0:15]
	ds_read_b64_tr_b16 v[112:113], v169 offset:4608
	ds_read_b64_tr_b16 v[114:115], v169 offset:5760
	s_waitcnt vmcnt(0)
	ds_write_b128 v170, v[144:147]
	v_exp_f32_e32 v128, v128
	v_exp_f32_e32 v129, v129
	v_add_f32_e32 v173, v173, v128
	v_add_f32_e32 v173, v173, v129
	v_cvt_pk_bf16_f32 v128, v128, v129
	s_waitcnt lgkmcnt(7)
	v_mfma_f32_32x32x16_bf16 v[16:31], v[64:67], v[116:119], v[16:31]
	ds_read_b64_tr_b16 v[116:117], v169 offset:4672
	ds_read_b64_tr_b16 v[118:119], v169 offset:5824
	ds_write_b128 v171, v[148:151]
	v_exp_f32_e32 v130, v130
	v_exp_f32_e32 v131, v131
	v_add_f32_e32 v173, v173, v130
	v_add_f32_e32 v173, v173, v131
	v_cvt_pk_bf16_f32 v129, v130, v131
	s_waitcnt lgkmcnt(8)
	v_mfma_f32_32x32x16_bf16 v[32:47], v[64:67], v[120:123], v[32:47]
	ds_read_b64_tr_b16 v[120:121], v169 offset:4736
	ds_read_b64_tr_b16 v[122:123], v169 offset:5888
	ds_write_b128 v170, v[152:155] offset:8704
	v_exp_f32_e32 v132, v132
	v_exp_f32_e32 v133, v133
	v_add_f32_e32 v173, v173, v132
	v_add_f32_e32 v173, v173, v133
	v_cvt_pk_bf16_f32 v130, v132, v133
	s_waitcnt lgkmcnt(9)
	v_mfma_f32_32x32x16_bf16 v[48:63], v[64:67], v[124:127], v[48:63]
	ds_read_b64_tr_b16 v[124:125], v169 offset:4800
	ds_read_b64_tr_b16 v[126:127], v169 offset:5952
	ds_write_b128 v171, v[156:159] offset:9216
	v_exp_f32_e32 v134, v134
	v_exp_f32_e32 v135, v135
	v_add_f32_e32 v173, v173, v134
	v_add_f32_e32 v173, v173, v135
	v_cvt_pk_bf16_f32 v131, v134, v135
	s_waitcnt lgkmcnt(10)
	v_mfma_f32_32x32x16_bf16 v[0:15], v[68:71], v[112:115], v[0:15]
	ds_read_b64_tr_b16 v[112:113], v169 offset:9216
	ds_read_b64_tr_b16 v[114:115], v169 offset:10368
	s_nop 0
	v_exp_f32_e32 v136, v136
	v_exp_f32_e32 v137, v137
	v_add_f32_e32 v173, v173, v136
	v_add_f32_e32 v173, v173, v137
	v_cvt_pk_bf16_f32 v132, v136, v137
	s_waitcnt lgkmcnt(9)
	v_mfma_f32_32x32x16_bf16 v[16:31], v[68:71], v[116:119], v[16:31]
	ds_read_b64_tr_b16 v[116:117], v169 offset:9280
	ds_read_b64_tr_b16 v[118:119], v169 offset:10432
	s_nop 0
	v_exp_f32_e32 v138, v138
	v_exp_f32_e32 v139, v139
	v_add_f32_e32 v173, v173, v138
	v_add_f32_e32 v173, v173, v139
	v_cvt_pk_bf16_f32 v133, v138, v139
	s_waitcnt lgkmcnt(8)
	v_mfma_f32_32x32x16_bf16 v[32:47], v[68:71], v[120:123], v[32:47]
	ds_read_b64_tr_b16 v[120:121], v169 offset:9344
	ds_read_b64_tr_b16 v[122:123], v169 offset:10496
	s_nop 0
	v_exp_f32_e32 v140, v140
	v_exp_f32_e32 v141, v141
	v_add_f32_e32 v173, v173, v140
	v_add_f32_e32 v173, v173, v141
	v_cvt_pk_bf16_f32 v134, v140, v141
	s_waitcnt lgkmcnt(7)
	v_mfma_f32_32x32x16_bf16 v[48:63], v[68:71], v[124:127], v[48:63]
	ds_read_b64_tr_b16 v[124:125], v169 offset:9408
	ds_read_b64_tr_b16 v[126:127], v169 offset:10560
	s_nop 0
	v_exp_f32_e32 v142, v142
	v_exp_f32_e32 v143, v143
	v_add_f32_e32 v173, v173, v142
	v_add_f32_e32 v173, v173, v143
	v_cvt_pk_bf16_f32 v135, v142, v143
	v_lshrrev_b32_e32 v174, v175, v174
	s_waitcnt lgkmcnt(6)
; #define LAS __attribute__((address_space(3)))
; __device__ __forceinline__ unsigned pk2(float lo, float hi) { return pg8::cvt_pk_bf16(lo, hi); }
; #define LDS_WAIT() asm volatile("s_waitcnt lgkmcnt(0)" ::: "memory")
; __device__ __forceinline__ s16x4 vtr(const LAS unsigned char* p) { return __builtin_bit_cast(s16x4, __builtin_amdgcn_ds_read_tr16_b64_v4i16((LAS s16x4*)p)); }
; __device__ __forceinline__ void dsa_unit(const bf16* QB, const int* SEL, bf16* AO, int b, int kvh, int t, LAS unsigned char* wl, int lane) {
;     ...
;         for (int kb = 0; kb < 8; ++kb) { const float e = __builtin_amdgcn_exp2f(lg[kb][g] - m); lg[kb][g] = e; s += e; }
;         s += __shfl_xor(s, 1); s += __shfl_xor(s, 2); s += __shfl_xor(s, 4); s += __shfl_xor(s, 8); s += __shfl_xor(s, 16);
;         const float inv = 1.0f / s;
; #pragma unroll
;         for (int kb = 0; kb < 8; ++kb) if ((kb >> 2) == hi) pT[g * 256 + 32 * kb + n] = (bf16)(pk2(lg[kb][g] * inv, 0.f) & 0xffffu);
;     }
;     f32x4v o[8];
; #pragma unroll
;     for (int c = 0; c < 8; ++c) o[c] = (f32x4v){0.f, 0.f, 0.f, 0.f};
;     const LAS unsigned char* vtb = buf + (8 * kq + (l15 >> 2)) * 288 + (lane & 3) * 8;
;     LAS unsigned char* vdst = buf + r4 * 288 + c16 * 16;
;     const LAS bf16* pfp = pT + (l15 & 3) * 256 + 8 * kq;
; #pragma unroll
;     for (int ch = 0; ch < 8; ++ch) {
; #pragma unroll
;         for (int i = 0; i < 8; ++i) *(LAS bf16x8*)(vdst + (4 * i) * 288) = vr[ch % 3][i];
;         if (ch + 3 < 8) {
; #pragma unroll
;             for (int i = 0; i < 8; ++i) vr[ch % 3][i] = *(const bf16x8*)(vg + (size_t)il[32 * (ch + 3) + 4 * i + r4] * NBP);
;         }
;         const bf16x8 pf = *(const LAS bf16x8*)(pfp + 32 * ch);
;         LDS_WAIT();
; #pragma unroll
;         for (int c = 0; c < 8; ++c) {
;             const s16x4 lo = vtr(vtb + c * 32), hh = vtr(vtb + 4 * 288 + c * 32);
;             o[c] = __builtin_amdgcn_mfma_f32_16x16x32_bf16(pf, (bf16x8){lo[0], lo[1], lo[2], lo[3], hh[0], hh[1], hh[2], hh[3]}, o[c], 0, 0, 0);
;         }
;         LDS_WAIT();
;     }
	v_mfma_f32_32x32x16_bf16 v[0:15], v[128:131], v[112:115], v[0:15]
	ds_read_b64_tr_b16 v[112:113], v169 offset:13824
	ds_read_b64_tr_b16 v[114:115], v169 offset:14976
	v_bfe_i32 v178, v174, 0, 1
	v_bfi_b32 v64, v178, v176, s13
	v_bfe_i32 v179, v174, 1, 1
	v_bfi_b32 v65, v179, v176, s13
	s_waitcnt lgkmcnt(6)
	v_mfma_f32_32x32x16_bf16 v[16:31], v[128:131], v[116:119], v[16:31]
	ds_read_b64_tr_b16 v[116:117], v169 offset:13888
	ds_read_b64_tr_b16 v[118:119], v169 offset:15040
	v_bfe_i32 v178, v174, 2, 1
	v_bfi_b32 v66, v178, v176, s13
	v_bfe_i32 v179, v174, 3, 1
	v_bfi_b32 v67, v179, v176, s13
	s_waitcnt lgkmcnt(6)
	v_mfma_f32_32x32x16_bf16 v[32:47], v[128:131], v[120:123], v[32:47]
	ds_read_b64_tr_b16 v[120:121], v169 offset:13952
	ds_read_b64_tr_b16 v[122:123], v169 offset:15104
	v_bfe_i32 v178, v174, 4, 1
	v_bfi_b32 v68, v178, v176, s13
	v_bfe_i32 v179, v174, 5, 1
	v_bfi_b32 v69, v179, v176, s13
	s_waitcnt lgkmcnt(6)
	v_mfma_f32_32x32x16_bf16 v[48:63], v[128:131], v[124:127], v[48:63]
	ds_read_b64_tr_b16 v[124:125], v169 offset:14016
	ds_read_b64_tr_b16 v[126:127], v169 offset:15168
	v_bfe_i32 v178, v174, 6, 1
	v_bfi_b32 v70, v178, v176, s13
	v_bfe_i32 v179, v174, 7, 1
	v_bfi_b32 v71, v179, v176, s13
	s_waitcnt lgkmcnt(6)
	v_mfma_f32_32x32x16_bf16 v[0:15], v[132:135], v[112:115], v[0:15]
	v_bfe_i32 v178, v174, 16, 1
	v_bfi_b32 v72, v178, v176, s13
	v_bfe_i32 v179, v174, 17, 1
	v_bfi_b32 v73, v179, v176, s13
	s_waitcnt lgkmcnt(4)
	v_mfma_f32_32x32x16_bf16 v[16:31], v[132:135], v[116:119], v[16:31]
	v_bfe_i32 v178, v174, 18, 1
	v_bfi_b32 v74, v178, v176, s13
	v_bfe_i32 v179, v174, 19, 1
	v_bfi_b32 v75, v179, v176, s13
	s_waitcnt lgkmcnt(2)
	v_mfma_f32_32x32x16_bf16 v[32:47], v[132:135], v[120:123], v[32:47]
	v_bfe_i32 v178, v174, 20, 1
	v_bfi_b32 v76, v178, v176, s13
	v_bfe_i32 v179, v174, 21, 1
	v_bfi_b32 v77, v179, v176, s13
	s_waitcnt lgkmcnt(0)
	v_mfma_f32_32x32x16_bf16 v[48:63], v[132:135], v[124:127], v[48:63]
	v_bfe_i32 v178, v174, 22, 1
	v_bfi_b32 v78, v178, v176, s13
	v_bfe_i32 v179, v174, 23, 1
	v_bfi_b32 v79, v179, v176, s13
	s_waitcnt lgkmcnt(0)
	s_barrier
	s_mov_b32 s25, s10
	s_mov_b32 s10, s11
	s_mov_b32 s11, s25
	v_add_u32_e32 v172, 8, v172
	s_mov_b32 s9, s24
	s_cmp_lt_u32 s9, s8
	s_cbranch_scc1 .Ldsa_it
	v_xor_b32_e32 v178, 32, v206
	v_lshlrev_b32_e32 v178, 2, v178
	ds_bpermute_b32 v179, v178, v173
	s_waitcnt lgkmcnt(0)
	v_add_f32_e32 v173, v173, v179
	v_rcp_f32_e32 v173, v173
	s_nop 0
	v_and_b32_e32 v178, 31, v206
	v_lshlrev_b32_e32 v178, 2, v178
	s_lshl_b32 s24, s0, 7
	s_add_u32 s24, s24, 0x1a000
	v_add_u32_e32 v178, s24, v178
	ds_write_b32 v178, v173
	v_lshl_add_u32 v179, v175, 1, s24
	s_waitcnt lgkmcnt(0)
	ds_read_b128 v[112:115], v179 offset:0
	ds_read_b128 v[116:119], v179 offset:32
	ds_read_b128 v[120:123], v179 offset:64
	ds_read_b128 v[124:127], v179 offset:96
	v_and_b32_e32 v178, 31, v206
	v_lshlrev_b32_e32 v178, 1, v178
	v_mul_u32_u24_e32 v179, 0x88, v175
	v_add3_u32 v178, v178, v179, s45
	v_lshrrev_b32_e32 v179, 4, v206
	v_mul_u32_u24_e32 v182, 0x110, v179
	v_and_b32_e32 v172, 15, v206
	v_lshl_add_u32 v182, v172, 4, v182
	v_add_u32_e32 v174, s45, v182
	s_add_u32 s24, s44, s7
	s_add_u32 s24, s24, s4
	s_lshr_b32 s25, s24, 20
	s_lshl_b32 s24, s24, 12
	s_add_u32 s24, s24, s67
	s_addc_u32 s25, s25, s85
	s_lshl_b32 s26, s5, 10
	s_add_u32 s24, s24, s26
	s_addc_u32 s25, s25, 0
	v_lshlrev_b32_e32 v179, 8, v179
	v_lshl_add_u32 v182, v172, 4, v179
	v_lshl_add_u64 v[144:145], s[24:25], 0, v[182:183]
	s_movk_i32 s26, 0x1000
	s_mov_b32 s27, 0
	s_waitcnt lgkmcnt(0)
; __device__ __forceinline__ unsigned pk2(float lo, float hi) { return pg8::cvt_pk_bf16(lo, hi); }
; __device__ __forceinline__ void dsa_unit(const bf16* QB, const int* SEL, bf16* AO, int b, int kvh, int t, LAS unsigned char* wl, int lane) {
;     ...
;         const float inv = 1.0f / s;
; #pragma unroll
;         for (int kb = 0; kb < 8; ++kb) if ((kb >> 2) == hi) pT[g * 256 + 32 * kb + n] = (bf16)(pk2(lg[kb][g] * inv, 0.f) & 0xffffu);
;     ...
;     bf16* op = AO + row * D + (kvh * 4) * 128 + 16 * kq + l15;
; #pragma unroll
;     for (int i = 0; i < 2; ++i)
; #pragma unroll
;         for (int g = 0; g < 4; ++g) {
;             const float v = (kq == 0) ? o[4 * i][g] : (kq == 1) ? o[4 * i + 1][g] : (kq == 2) ? o[4 * i + 2][g] : o[4 * i + 3][g];
;             op[g * 128 + 64 * i] = (bf16)(pk2(v, 0.f) & 0xffffu);
;         }
	v_pk_mul_f32 v[0:1], v[0:1], v[112:113]
	v_pk_mul_f32 v[2:3], v[2:3], v[114:115]
	v_pk_mul_f32 v[4:5], v[4:5], v[116:117]
	v_pk_mul_f32 v[6:7], v[6:7], v[118:119]
	v_pk_mul_f32 v[8:9], v[8:9], v[120:121]
	v_pk_mul_f32 v[10:11], v[10:11], v[122:123]
	v_pk_mul_f32 v[12:13], v[12:13], v[124:125]
	v_pk_mul_f32 v[14:15], v[14:15], v[126:127]
	v_pk_mul_f32 v[16:17], v[16:17], v[112:113]
	v_pk_mul_f32 v[18:19], v[18:19], v[114:115]
	v_pk_mul_f32 v[20:21], v[20:21], v[116:117]
	v_pk_mul_f32 v[22:23], v[22:23], v[118:119]
	v_pk_mul_f32 v[24:25], v[24:25], v[120:121]
	v_pk_mul_f32 v[26:27], v[26:27], v[122:123]
	v_pk_mul_f32 v[28:29], v[28:29], v[124:125]
	v_pk_mul_f32 v[30:31], v[30:31], v[126:127]
	v_pk_mul_f32 v[32:33], v[32:33], v[112:113]
	v_pk_mul_f32 v[34:35], v[34:35], v[114:115]
	v_pk_mul_f32 v[36:37], v[36:37], v[116:117]
	v_pk_mul_f32 v[38:39], v[38:39], v[118:119]
	v_pk_mul_f32 v[40:41], v[40:41], v[120:121]
	v_pk_mul_f32 v[42:43], v[42:43], v[122:123]
	v_pk_mul_f32 v[44:45], v[44:45], v[124:125]
	v_pk_mul_f32 v[46:47], v[46:47], v[126:127]
	v_pk_mul_f32 v[48:49], v[48:49], v[112:113]
	v_pk_mul_f32 v[50:51], v[50:51], v[114:115]
	v_pk_mul_f32 v[52:53], v[52:53], v[116:117]
	v_pk_mul_f32 v[54:55], v[54:55], v[118:119]
	v_pk_mul_f32 v[56:57], v[56:57], v[120:121]
	v_pk_mul_f32 v[58:59], v[58:59], v[122:123]
	v_pk_mul_f32 v[60:61], v[60:61], v[124:125]
	v_pk_mul_f32 v[62:63], v[62:63], v[126:127]
	v_cvt_pk_bf16_f32 v64, v0, v1
	v_cvt_pk_bf16_f32 v65, v2, v3
	v_cvt_pk_bf16_f32 v66, v4, v5
	v_cvt_pk_bf16_f32 v67, v6, v7
	v_cvt_pk_bf16_f32 v68, v8, v9
	v_cvt_pk_bf16_f32 v69, v10, v11
	v_cvt_pk_bf16_f32 v70, v12, v13
	v_cvt_pk_bf16_f32 v71, v14, v15
	ds_write_b16 v178, v64 offset:0
	ds_write_b16_d16_hi v178, v64 offset:272
	ds_write_b16 v178, v65 offset:544
	ds_write_b16_d16_hi v178, v65 offset:816
	ds_write_b16 v178, v66 offset:2176
	ds_write_b16_d16_hi v178, v66 offset:2448
	ds_write_b16 v178, v67 offset:2720
	ds_write_b16_d16_hi v178, v67 offset:2992
	ds_write_b16 v178, v68 offset:4352
	ds_write_b16_d16_hi v178, v68 offset:4624
	ds_write_b16 v178, v69 offset:4896
	ds_write_b16_d16_hi v178, v69 offset:5168
	ds_write_b16 v178, v70 offset:6528
	ds_write_b16_d16_hi v178, v70 offset:6800
	ds_write_b16 v178, v71 offset:7072
	ds_write_b16_d16_hi v178, v71 offset:7344
	v_cvt_pk_bf16_f32 v72, v16, v17
	v_cvt_pk_bf16_f32 v73, v18, v19
	v_cvt_pk_bf16_f32 v74, v20, v21
	v_cvt_pk_bf16_f32 v75, v22, v23
	v_cvt_pk_bf16_f32 v76, v24, v25
	v_cvt_pk_bf16_f32 v77, v26, v27
	v_cvt_pk_bf16_f32 v78, v28, v29
	v_cvt_pk_bf16_f32 v79, v30, v31
	ds_write_b16 v178, v72 offset:64
	ds_write_b16_d16_hi v178, v72 offset:336
	ds_write_b16 v178, v73 offset:608
	ds_write_b16_d16_hi v178, v73 offset:880
	ds_write_b16 v178, v74 offset:2240
	ds_write_b16_d16_hi v178, v74 offset:2512
	ds_write_b16 v178, v75 offset:2784
	ds_write_b16_d16_hi v178, v75 offset:3056
	ds_write_b16 v178, v76 offset:4416
	ds_write_b16_d16_hi v178, v76 offset:4688
	ds_write_b16 v178, v77 offset:4960
	ds_write_b16_d16_hi v178, v77 offset:5232
	ds_write_b16 v178, v78 offset:6592
	ds_write_b16_d16_hi v178, v78 offset:6864
	ds_write_b16 v178, v79 offset:7136
	ds_write_b16_d16_hi v178, v79 offset:7408
	v_cvt_pk_bf16_f32 v128, v32, v33
	v_cvt_pk_bf16_f32 v129, v34, v35
	v_cvt_pk_bf16_f32 v130, v36, v37
	v_cvt_pk_bf16_f32 v131, v38, v39
	v_cvt_pk_bf16_f32 v132, v40, v41
	v_cvt_pk_bf16_f32 v133, v42, v43
	v_cvt_pk_bf16_f32 v134, v44, v45
	v_cvt_pk_bf16_f32 v135, v46, v47
	ds_write_b16 v178, v128 offset:128
	ds_write_b16_d16_hi v178, v128 offset:400
	ds_write_b16 v178, v129 offset:672
	ds_write_b16_d16_hi v178, v129 offset:944
	ds_write_b16 v178, v130 offset:2304
	ds_write_b16_d16_hi v178, v130 offset:2576
	ds_write_b16 v178, v131 offset:2848
	ds_write_b16_d16_hi v178, v131 offset:3120
	ds_write_b16 v178, v132 offset:4480
	ds_write_b16_d16_hi v178, v132 offset:4752
	ds_write_b16 v178, v133 offset:5024
	ds_write_b16_d16_hi v178, v133 offset:5296
	ds_write_b16 v178, v134 offset:6656
	ds_write_b16_d16_hi v178, v134 offset:6928
	ds_write_b16 v178, v135 offset:7200
	ds_write_b16_d16_hi v178, v135 offset:7472
	v_cvt_pk_bf16_f32 v136, v48, v49
	v_cvt_pk_bf16_f32 v137, v50, v51
	v_cvt_pk_bf16_f32 v138, v52, v53
	v_cvt_pk_bf16_f32 v139, v54, v55
	v_cvt_pk_bf16_f32 v140, v56, v57
	v_cvt_pk_bf16_f32 v141, v58, v59
	v_cvt_pk_bf16_f32 v142, v60, v61
	v_cvt_pk_bf16_f32 v143, v62, v63
	ds_write_b16 v178, v136 offset:192
	ds_write_b16_d16_hi v178, v136 offset:464
	ds_write_b16 v178, v137 offset:736
	ds_write_b16_d16_hi v178, v137 offset:1008
	ds_write_b16 v178, v138 offset:2368
	ds_write_b16_d16_hi v178, v138 offset:2640
	ds_write_b16 v178, v139 offset:2912
	ds_write_b16_d16_hi v178, v139 offset:3184
	ds_write_b16 v178, v140 offset:4544
	ds_write_b16_d16_hi v178, v140 offset:4816
	ds_write_b16 v178, v141 offset:5088
	ds_write_b16_d16_hi v178, v141 offset:5360
	ds_write_b16 v178, v142 offset:6720
	ds_write_b16_d16_hi v178, v142 offset:6992
	ds_write_b16 v178, v143 offset:7264
	ds_write_b16_d16_hi v178, v143 offset:7536
	s_waitcnt lgkmcnt(0)
	ds_read_b128 v[80:83], v174 offset:0
	ds_read_b128 v[84:87], v174 offset:1088
	ds_read_b128 v[88:91], v174 offset:2176
	ds_read_b128 v[92:95], v174 offset:3264
	ds_read_b128 v[96:99], v174 offset:4352
	ds_read_b128 v[100:103], v174 offset:5440
	ds_read_b128 v[104:107], v174 offset:6528
	ds_read_b128 v[108:111], v174 offset:7616
	s_waitcnt lgkmcnt(7)
	global_store_dwordx4 v[144:145], v[80:83], off
	v_lshl_add_u64 v[144:145], v[144:145], 0, s[26:27]
	s_waitcnt lgkmcnt(6)
	global_store_dwordx4 v[144:145], v[84:87], off
	v_lshl_add_u64 v[144:145], v[144:145], 0, s[26:27]
	s_waitcnt lgkmcnt(5)
	global_store_dwordx4 v[144:145], v[88:91], off
	v_lshl_add_u64 v[144:145], v[144:145], 0, s[26:27]
	s_waitcnt lgkmcnt(4)
	global_store_dwordx4 v[144:145], v[92:95], off
	v_lshl_add_u64 v[144:145], v[144:145], 0, s[26:27]
	s_waitcnt lgkmcnt(3)
	global_store_dwordx4 v[144:145], v[96:99], off
	v_lshl_add_u64 v[144:145], v[144:145], 0, s[26:27]
	s_waitcnt lgkmcnt(2)
	global_store_dwordx4 v[144:145], v[100:103], off
	v_lshl_add_u64 v[144:145], v[144:145], 0, s[26:27]
	s_waitcnt lgkmcnt(1)
	global_store_dwordx4 v[144:145], v[104:107], off
	v_lshl_add_u64 v[144:145], v[144:145], 0, s[26:27]
	s_waitcnt lgkmcnt(0)
	global_store_dwordx4 v[144:145], v[108:111], off
	s_mov_b32 s21, s35
	s_branch .Ldsa_run
